# grid barrier: the releasing leader no longer drains its fire-and-forget release atomics before re-joining its workgroup (two s_waitcnt vmcnt(0) removed per barrier)
# speedup vs baseline: 1.0080x; 1.0003x over previous
.LBB0_260:
	s_or_b64 exec, exec, s[4:5]
	s_mov_b64 s[4:5], exec
	v_mbcnt_lo_u32_b32 v0, s4, 0
	v_mbcnt_hi_u32_b32 v0, s5, v0
	v_cmp_eq_u32_e32 vcc, 0, v0
	s_and_saveexec_b64 s[6:7], vcc
	s_cbranch_execz .LBB0_262
	s_bcnt1_i32_b64 s4, s[4:5]
	v_mov_b32_e32 v0, 0x2000
	v_mov_b32_e32 v1, s4
.LBB0_262:
	s_or_b64 exec, exec, s[6:7]
.LBB0_263:
	s_or_b64 exec, exec, s[0:1]
	s_waitcnt lgkmcnt(0)
	s_barrier

.LBB0_333:
	s_or_b64 exec, exec, s[6:7]
.LBB0_334:
	s_or_b64 exec, exec, s[0:1]
	s_waitcnt lgkmcnt(0)
	s_barrier

.LBB0_513:
	s_or_b64 exec, exec, s[6:7]
.LBB0_514:
	s_or_b64 exec, exec, s[0:1]
	s_waitcnt lgkmcnt(0)
	s_barrier

.LBB0_930:
	s_or_b64 exec, exec, s[6:7]
.LBB0_931:
	s_or_b64 exec, exec, s[0:1]
	s_waitcnt lgkmcnt(0)
	s_barrier

.LBB0_1055:
	s_or_b64 exec, exec, s[6:7]
.LBB0_1056:
	s_or_b64 exec, exec, s[0:1]
	s_waitcnt lgkmcnt(0)
	s_barrier

.LBB0_1156:
	s_or_b64 exec, exec, s[6:7]
.LBB0_1157:
	s_or_b64 exec, exec, s[0:1]
	s_waitcnt lgkmcnt(0)
	s_barrier

.LBB0_1238:
	s_or_b64 exec, exec, s[6:7]
.LBB0_1239:
	s_or_b64 exec, exec, s[0:1]
	s_waitcnt lgkmcnt(0)
	s_barrier

.LBB0_1309:
	s_or_b64 exec, exec, s[6:7]
.LBB0_1310:
	s_or_b64 exec, exec, s[0:1]
	s_waitcnt lgkmcnt(0)
	s_barrier

.LBB0_1406:
	s_or_b64 exec, exec, s[6:7]
.LBB0_1407:
	s_or_b64 exec, exec, s[0:1]
	s_waitcnt lgkmcnt(0)
	s_barrier

.LBB0_1485:
	s_or_b64 exec, exec, s[6:7]
.LBB0_1486:
	s_or_b64 exec, exec, s[0:1]
	s_waitcnt lgkmcnt(0)
	s_barrier
